# prologue adaLN GEMV: rolling reload pipeline keeps 8 row loads in flight (on top of SCAN rewrite)
# speedup vs baseline: 1.0006x; 1.0006x over previous
.LBB0_21:
	v_add_co_u32_e32 v140, vcc, s45, v30
	s_nop 1
	v_addc_co_u32_e32 v141, vcc, -1, v31, vcc
	v_add_co_u32_e32 v142, vcc, s46, v30
	s_nop 1
	v_addc_co_u32_e32 v143, vcc, -1, v31, vcc
	v_add_co_u32_e32 v144, vcc, s47, v30
	s_nop 1
	v_addc_co_u32_e32 v145, vcc, -1, v31, vcc
	v_add_co_u32_e32 v146, vcc, s48, v30
	s_nop 1
	v_addc_co_u32_e32 v147, vcc, -1, v31, vcc
	v_mov_b32_e32 v148, v30
	v_mov_b32_e32 v149, v31
	v_add_co_u32_e32 v150, vcc, s43, v30
	s_nop 1
	v_addc_co_u32_e32 v151, vcc, 0, v31, vcc
	v_add_co_u32_e32 v152, vcc, s49, v30
	s_nop 1
	v_addc_co_u32_e32 v153, vcc, 0, v31, vcc
	v_add_co_u32_e32 v154, vcc, s50, v30
	s_nop 1
	v_addc_co_u32_e32 v155, vcc, 0, v31, vcc
	global_load_dwordx4 v[48:51], v[140:141], off
	global_load_dwordx4 v[52:55], v[142:143], off
	global_load_dwordx4 v[56:59], v[144:145], off
	global_load_dwordx4 v[60:63], v[146:147], off
	global_load_dwordx4 v[44:47], v[148:149], off
	global_load_dwordx4 v[64:67], v[150:151], off
	global_load_dwordx4 v[68:71], v[152:153], off
	global_load_dwordx4 v[72:75], v[154:155], off
.Lgemv0_loop:
	v_add_u32_e32 v77, s36, v36
	ds_bpermute_b32 v76, v77, v40
	ds_bpermute_b32 v78, v77, v41
	ds_bpermute_b32 v80, v77, v42
	ds_bpermute_b32 v82, v77, v43
	ds_bpermute_b32 v84, v77, v40 offset:4
	ds_bpermute_b32 v86, v77, v41 offset:4
	ds_bpermute_b32 v88, v77, v42 offset:4
	ds_bpermute_b32 v90, v77, v43 offset:4
	ds_bpermute_b32 v92, v77, v40 offset:8
	ds_bpermute_b32 v94, v77, v41 offset:8
	ds_bpermute_b32 v96, v77, v42 offset:8
	ds_bpermute_b32 v98, v77, v43 offset:8
	ds_bpermute_b32 v100, v77, v40 offset:12
	ds_bpermute_b32 v102, v77, v41 offset:12
	ds_bpermute_b32 v104, v77, v42 offset:12
	ds_bpermute_b32 v106, v77, v43 offset:12
	ds_bpermute_b32 v108, v77, v40 offset:16
	ds_bpermute_b32 v110, v77, v41 offset:16
	ds_bpermute_b32 v112, v77, v42 offset:16
	ds_bpermute_b32 v114, v77, v43 offset:16
	ds_bpermute_b32 v116, v77, v40 offset:20
	ds_bpermute_b32 v118, v77, v41 offset:20
	ds_bpermute_b32 v120, v77, v42 offset:20
	ds_bpermute_b32 v122, v77, v43 offset:20
	ds_bpermute_b32 v124, v77, v40 offset:24
	ds_bpermute_b32 v126, v77, v41 offset:24
	ds_bpermute_b32 v128, v77, v42 offset:24
	ds_bpermute_b32 v130, v77, v43 offset:24
	ds_bpermute_b32 v132, v77, v40 offset:28
	ds_bpermute_b32 v134, v77, v41 offset:28
	ds_bpermute_b32 v136, v77, v42 offset:28
	ds_bpermute_b32 v138, v77, v43 offset:28
	s_add_i32 s36, s36, 32
	s_cmpk_eq_i32 s36, 0xe0
	s_waitcnt vmcnt(7)
	s_waitcnt lgkmcnt(14)
	v_pk_fma_f32 v[4:5], v[50:51], v[76:77], v[4:5] op_sel_hi:[1,0,1]
	v_pk_fma_f32 v[2:3], v[48:49], v[76:77], v[2:3] op_sel_hi:[1,0,1]
	v_pk_fma_f32 v[8:9], v[50:51], v[78:79], v[8:9] op_sel_hi:[1,0,1]
	v_pk_fma_f32 v[6:7], v[48:49], v[78:79], v[6:7] op_sel_hi:[1,0,1]
	v_pk_fma_f32 v[12:13], v[50:51], v[80:81], v[12:13] op_sel_hi:[1,0,1]
	v_pk_fma_f32 v[10:11], v[48:49], v[80:81], v[10:11] op_sel_hi:[1,0,1]
	v_pk_fma_f32 v[16:17], v[50:51], v[82:83], v[16:17] op_sel_hi:[1,0,1]
	v_pk_fma_f32 v[14:15], v[48:49], v[82:83], v[14:15] op_sel_hi:[1,0,1]
	v_lshl_add_u64 v[140:141], v[140:141], 0, s[28:29]
	global_load_dwordx4 v[48:51], v[140:141], off
	s_waitcnt vmcnt(7)
	v_pk_fma_f32 v[4:5], v[54:55], v[84:85], v[4:5] op_sel_hi:[1,0,1]
	v_pk_fma_f32 v[2:3], v[52:53], v[84:85], v[2:3] op_sel_hi:[1,0,1]
	v_pk_fma_f32 v[8:9], v[54:55], v[86:87], v[8:9] op_sel_hi:[1,0,1]
	v_pk_fma_f32 v[6:7], v[52:53], v[86:87], v[6:7] op_sel_hi:[1,0,1]
	v_pk_fma_f32 v[12:13], v[54:55], v[88:89], v[12:13] op_sel_hi:[1,0,1]
	v_pk_fma_f32 v[10:11], v[52:53], v[88:89], v[10:11] op_sel_hi:[1,0,1]
	v_pk_fma_f32 v[16:17], v[54:55], v[90:91], v[16:17] op_sel_hi:[1,0,1]
	v_pk_fma_f32 v[14:15], v[52:53], v[90:91], v[14:15] op_sel_hi:[1,0,1]
	v_lshl_add_u64 v[142:143], v[142:143], 0, s[28:29]
	global_load_dwordx4 v[52:55], v[142:143], off
	s_waitcnt vmcnt(7)
	v_pk_fma_f32 v[4:5], v[58:59], v[92:93], v[4:5] op_sel_hi:[1,0,1]
	v_pk_fma_f32 v[2:3], v[56:57], v[92:93], v[2:3] op_sel_hi:[1,0,1]
	v_pk_fma_f32 v[8:9], v[58:59], v[94:95], v[8:9] op_sel_hi:[1,0,1]
	v_pk_fma_f32 v[6:7], v[56:57], v[94:95], v[6:7] op_sel_hi:[1,0,1]
	v_pk_fma_f32 v[12:13], v[58:59], v[96:97], v[12:13] op_sel_hi:[1,0,1]
	v_pk_fma_f32 v[10:11], v[56:57], v[96:97], v[10:11] op_sel_hi:[1,0,1]
	v_pk_fma_f32 v[16:17], v[58:59], v[98:99], v[16:17] op_sel_hi:[1,0,1]
	v_pk_fma_f32 v[14:15], v[56:57], v[98:99], v[14:15] op_sel_hi:[1,0,1]
	v_lshl_add_u64 v[144:145], v[144:145], 0, s[28:29]
	global_load_dwordx4 v[56:59], v[144:145], off
	s_waitcnt vmcnt(7)
	v_pk_fma_f32 v[4:5], v[62:63], v[100:101], v[4:5] op_sel_hi:[1,0,1]
	v_pk_fma_f32 v[2:3], v[60:61], v[100:101], v[2:3] op_sel_hi:[1,0,1]
	v_pk_fma_f32 v[8:9], v[62:63], v[102:103], v[8:9] op_sel_hi:[1,0,1]
	v_pk_fma_f32 v[6:7], v[60:61], v[102:103], v[6:7] op_sel_hi:[1,0,1]
	v_pk_fma_f32 v[12:13], v[62:63], v[104:105], v[12:13] op_sel_hi:[1,0,1]
	v_pk_fma_f32 v[10:11], v[60:61], v[104:105], v[10:11] op_sel_hi:[1,0,1]
	v_pk_fma_f32 v[16:17], v[62:63], v[106:107], v[16:17] op_sel_hi:[1,0,1]
	v_pk_fma_f32 v[14:15], v[60:61], v[106:107], v[14:15] op_sel_hi:[1,0,1]
	v_lshl_add_u64 v[146:147], v[146:147], 0, s[28:29]
	global_load_dwordx4 v[60:63], v[146:147], off
	s_waitcnt vmcnt(7)
	v_pk_fma_f32 v[4:5], v[46:47], v[108:109], v[4:5] op_sel_hi:[1,0,1]
	v_pk_fma_f32 v[2:3], v[44:45], v[108:109], v[2:3] op_sel_hi:[1,0,1]
	v_pk_fma_f32 v[8:9], v[46:47], v[110:111], v[8:9] op_sel_hi:[1,0,1]
	v_pk_fma_f32 v[6:7], v[44:45], v[110:111], v[6:7] op_sel_hi:[1,0,1]
	s_waitcnt lgkmcnt(13)
	v_pk_fma_f32 v[12:13], v[46:47], v[112:113], v[12:13] op_sel_hi:[1,0,1]
	v_pk_fma_f32 v[10:11], v[44:45], v[112:113], v[10:11] op_sel_hi:[1,0,1]
	s_waitcnt lgkmcnt(12)
	v_pk_fma_f32 v[16:17], v[46:47], v[114:115], v[16:17] op_sel_hi:[1,0,1]
	v_pk_fma_f32 v[14:15], v[44:45], v[114:115], v[14:15] op_sel_hi:[1,0,1]
	v_lshl_add_u64 v[148:149], v[148:149], 0, s[28:29]
	global_load_dwordx4 v[44:47], v[148:149], off
	s_waitcnt vmcnt(7)
	s_waitcnt lgkmcnt(11)
	v_pk_fma_f32 v[4:5], v[66:67], v[116:117], v[4:5] op_sel_hi:[1,0,1]
	v_pk_fma_f32 v[2:3], v[64:65], v[116:117], v[2:3] op_sel_hi:[1,0,1]
	s_waitcnt lgkmcnt(10)
	v_pk_fma_f32 v[8:9], v[66:67], v[118:119], v[8:9] op_sel_hi:[1,0,1]
	v_pk_fma_f32 v[6:7], v[64:65], v[118:119], v[6:7] op_sel_hi:[1,0,1]
	s_waitcnt lgkmcnt(9)
	v_pk_fma_f32 v[12:13], v[66:67], v[120:121], v[12:13] op_sel_hi:[1,0,1]
	v_pk_fma_f32 v[10:11], v[64:65], v[120:121], v[10:11] op_sel_hi:[1,0,1]
	s_waitcnt lgkmcnt(8)
	v_pk_fma_f32 v[16:17], v[66:67], v[122:123], v[16:17] op_sel_hi:[1,0,1]
	v_pk_fma_f32 v[14:15], v[64:65], v[122:123], v[14:15] op_sel_hi:[1,0,1]
	v_lshl_add_u64 v[150:151], v[150:151], 0, s[28:29]
	global_load_dwordx4 v[64:67], v[150:151], off
	s_waitcnt vmcnt(7)
	s_waitcnt lgkmcnt(7)
	v_pk_fma_f32 v[4:5], v[70:71], v[124:125], v[4:5] op_sel_hi:[1,0,1]
	v_pk_fma_f32 v[2:3], v[68:69], v[124:125], v[2:3] op_sel_hi:[1,0,1]
	s_waitcnt lgkmcnt(6)
	v_pk_fma_f32 v[8:9], v[70:71], v[126:127], v[8:9] op_sel_hi:[1,0,1]
	v_pk_fma_f32 v[6:7], v[68:69], v[126:127], v[6:7] op_sel_hi:[1,0,1]
	s_waitcnt lgkmcnt(5)
	v_pk_fma_f32 v[12:13], v[70:71], v[128:129], v[12:13] op_sel_hi:[1,0,1]
	v_pk_fma_f32 v[10:11], v[68:69], v[128:129], v[10:11] op_sel_hi:[1,0,1]
	s_waitcnt lgkmcnt(4)
	v_pk_fma_f32 v[16:17], v[70:71], v[130:131], v[16:17] op_sel_hi:[1,0,1]
	v_pk_fma_f32 v[14:15], v[68:69], v[130:131], v[14:15] op_sel_hi:[1,0,1]
	v_lshl_add_u64 v[152:153], v[152:153], 0, s[28:29]
	global_load_dwordx4 v[68:71], v[152:153], off
	s_waitcnt vmcnt(7)
	s_waitcnt lgkmcnt(3)
	v_pk_fma_f32 v[4:5], v[74:75], v[132:133], v[4:5] op_sel_hi:[1,0,1]
	v_pk_fma_f32 v[2:3], v[72:73], v[132:133], v[2:3] op_sel_hi:[1,0,1]
	s_waitcnt lgkmcnt(2)
	v_pk_fma_f32 v[8:9], v[74:75], v[134:135], v[8:9] op_sel_hi:[1,0,1]
	v_pk_fma_f32 v[6:7], v[72:73], v[134:135], v[6:7] op_sel_hi:[1,0,1]
	s_waitcnt lgkmcnt(1)
	v_pk_fma_f32 v[12:13], v[74:75], v[136:137], v[12:13] op_sel_hi:[1,0,1]
	v_pk_fma_f32 v[10:11], v[72:73], v[136:137], v[10:11] op_sel_hi:[1,0,1]
	s_waitcnt lgkmcnt(0)
	v_pk_fma_f32 v[16:17], v[74:75], v[138:139], v[16:17] op_sel_hi:[1,0,1]
	v_pk_fma_f32 v[14:15], v[72:73], v[138:139], v[14:15] op_sel_hi:[1,0,1]
	v_lshl_add_u64 v[154:155], v[154:155], 0, s[28:29]
	global_load_dwordx4 v[72:75], v[154:155], off
	s_cbranch_scc0 .Lgemv0_loop
	v_add_u32_e32 v77, s36, v36
	ds_bpermute_b32 v76, v77, v40
	ds_bpermute_b32 v78, v77, v41
	ds_bpermute_b32 v80, v77, v42
	ds_bpermute_b32 v82, v77, v43
	ds_bpermute_b32 v84, v77, v40 offset:4
	ds_bpermute_b32 v86, v77, v41 offset:4
	ds_bpermute_b32 v88, v77, v42 offset:4
	ds_bpermute_b32 v90, v77, v43 offset:4
	ds_bpermute_b32 v92, v77, v40 offset:8
	ds_bpermute_b32 v94, v77, v41 offset:8
	ds_bpermute_b32 v96, v77, v42 offset:8
	ds_bpermute_b32 v98, v77, v43 offset:8
	ds_bpermute_b32 v100, v77, v40 offset:12
	ds_bpermute_b32 v102, v77, v41 offset:12
	ds_bpermute_b32 v104, v77, v42 offset:12
	ds_bpermute_b32 v106, v77, v43 offset:12
	ds_bpermute_b32 v108, v77, v40 offset:16
	ds_bpermute_b32 v110, v77, v41 offset:16
	ds_bpermute_b32 v112, v77, v42 offset:16
	ds_bpermute_b32 v114, v77, v43 offset:16
	ds_bpermute_b32 v116, v77, v40 offset:20
	ds_bpermute_b32 v118, v77, v41 offset:20
	ds_bpermute_b32 v120, v77, v42 offset:20
	ds_bpermute_b32 v122, v77, v43 offset:20
	ds_bpermute_b32 v124, v77, v40 offset:24
	ds_bpermute_b32 v126, v77, v41 offset:24
	ds_bpermute_b32 v128, v77, v42 offset:24
	ds_bpermute_b32 v130, v77, v43 offset:24
	ds_bpermute_b32 v132, v77, v40 offset:28
	ds_bpermute_b32 v134, v77, v41 offset:28
	ds_bpermute_b32 v136, v77, v42 offset:28
	ds_bpermute_b32 v138, v77, v43 offset:28
	s_add_i32 s36, s36, 32
	s_waitcnt vmcnt(7)
	s_waitcnt lgkmcnt(14)
	v_pk_fma_f32 v[4:5], v[50:51], v[76:77], v[4:5] op_sel_hi:[1,0,1]
	v_pk_fma_f32 v[2:3], v[48:49], v[76:77], v[2:3] op_sel_hi:[1,0,1]
	v_pk_fma_f32 v[8:9], v[50:51], v[78:79], v[8:9] op_sel_hi:[1,0,1]
	v_pk_fma_f32 v[6:7], v[48:49], v[78:79], v[6:7] op_sel_hi:[1,0,1]
	v_pk_fma_f32 v[12:13], v[50:51], v[80:81], v[12:13] op_sel_hi:[1,0,1]
	v_pk_fma_f32 v[10:11], v[48:49], v[80:81], v[10:11] op_sel_hi:[1,0,1]
	v_pk_fma_f32 v[16:17], v[50:51], v[82:83], v[16:17] op_sel_hi:[1,0,1]
	v_pk_fma_f32 v[14:15], v[48:49], v[82:83], v[14:15] op_sel_hi:[1,0,1]
	s_waitcnt vmcnt(6)
	v_pk_fma_f32 v[4:5], v[54:55], v[84:85], v[4:5] op_sel_hi:[1,0,1]
	v_pk_fma_f32 v[2:3], v[52:53], v[84:85], v[2:3] op_sel_hi:[1,0,1]
	v_pk_fma_f32 v[8:9], v[54:55], v[86:87], v[8:9] op_sel_hi:[1,0,1]
	v_pk_fma_f32 v[6:7], v[52:53], v[86:87], v[6:7] op_sel_hi:[1,0,1]
	v_pk_fma_f32 v[12:13], v[54:55], v[88:89], v[12:13] op_sel_hi:[1,0,1]
	v_pk_fma_f32 v[10:11], v[52:53], v[88:89], v[10:11] op_sel_hi:[1,0,1]
	v_pk_fma_f32 v[16:17], v[54:55], v[90:91], v[16:17] op_sel_hi:[1,0,1]
	v_pk_fma_f32 v[14:15], v[52:53], v[90:91], v[14:15] op_sel_hi:[1,0,1]
	s_waitcnt vmcnt(5)
	v_pk_fma_f32 v[4:5], v[58:59], v[92:93], v[4:5] op_sel_hi:[1,0,1]
	v_pk_fma_f32 v[2:3], v[56:57], v[92:93], v[2:3] op_sel_hi:[1,0,1]
	v_pk_fma_f32 v[8:9], v[58:59], v[94:95], v[8:9] op_sel_hi:[1,0,1]
	v_pk_fma_f32 v[6:7], v[56:57], v[94:95], v[6:7] op_sel_hi:[1,0,1]
	v_pk_fma_f32 v[12:13], v[58:59], v[96:97], v[12:13] op_sel_hi:[1,0,1]
	v_pk_fma_f32 v[10:11], v[56:57], v[96:97], v[10:11] op_sel_hi:[1,0,1]
	v_pk_fma_f32 v[16:17], v[58:59], v[98:99], v[16:17] op_sel_hi:[1,0,1]
	v_pk_fma_f32 v[14:15], v[56:57], v[98:99], v[14:15] op_sel_hi:[1,0,1]
	s_waitcnt vmcnt(4)
	v_pk_fma_f32 v[4:5], v[62:63], v[100:101], v[4:5] op_sel_hi:[1,0,1]
	v_pk_fma_f32 v[2:3], v[60:61], v[100:101], v[2:3] op_sel_hi:[1,0,1]
	v_pk_fma_f32 v[8:9], v[62:63], v[102:103], v[8:9] op_sel_hi:[1,0,1]
	v_pk_fma_f32 v[6:7], v[60:61], v[102:103], v[6:7] op_sel_hi:[1,0,1]
	v_pk_fma_f32 v[12:13], v[62:63], v[104:105], v[12:13] op_sel_hi:[1,0,1]
	v_pk_fma_f32 v[10:11], v[60:61], v[104:105], v[10:11] op_sel_hi:[1,0,1]
	v_pk_fma_f32 v[16:17], v[62:63], v[106:107], v[16:17] op_sel_hi:[1,0,1]
	v_pk_fma_f32 v[14:15], v[60:61], v[106:107], v[14:15] op_sel_hi:[1,0,1]
	s_waitcnt vmcnt(3)
	v_pk_fma_f32 v[4:5], v[46:47], v[108:109], v[4:5] op_sel_hi:[1,0,1]
	v_pk_fma_f32 v[2:3], v[44:45], v[108:109], v[2:3] op_sel_hi:[1,0,1]
	v_pk_fma_f32 v[8:9], v[46:47], v[110:111], v[8:9] op_sel_hi:[1,0,1]
	v_pk_fma_f32 v[6:7], v[44:45], v[110:111], v[6:7] op_sel_hi:[1,0,1]
	s_waitcnt lgkmcnt(13)
	v_pk_fma_f32 v[12:13], v[46:47], v[112:113], v[12:13] op_sel_hi:[1,0,1]
	v_pk_fma_f32 v[10:11], v[44:45], v[112:113], v[10:11] op_sel_hi:[1,0,1]
	s_waitcnt lgkmcnt(12)
	v_pk_fma_f32 v[16:17], v[46:47], v[114:115], v[16:17] op_sel_hi:[1,0,1]
	v_pk_fma_f32 v[14:15], v[44:45], v[114:115], v[14:15] op_sel_hi:[1,0,1]
	s_waitcnt vmcnt(2)
	s_waitcnt lgkmcnt(11)
	v_pk_fma_f32 v[4:5], v[66:67], v[116:117], v[4:5] op_sel_hi:[1,0,1]
	v_pk_fma_f32 v[2:3], v[64:65], v[116:117], v[2:3] op_sel_hi:[1,0,1]
	s_waitcnt lgkmcnt(10)
	v_pk_fma_f32 v[8:9], v[66:67], v[118:119], v[8:9] op_sel_hi:[1,0,1]
	v_pk_fma_f32 v[6:7], v[64:65], v[118:119], v[6:7] op_sel_hi:[1,0,1]
	s_waitcnt lgkmcnt(9)
	v_pk_fma_f32 v[12:13], v[66:67], v[120:121], v[12:13] op_sel_hi:[1,0,1]
	v_pk_fma_f32 v[10:11], v[64:65], v[120:121], v[10:11] op_sel_hi:[1,0,1]
	s_waitcnt lgkmcnt(8)
	v_pk_fma_f32 v[16:17], v[66:67], v[122:123], v[16:17] op_sel_hi:[1,0,1]
	v_pk_fma_f32 v[14:15], v[64:65], v[122:123], v[14:15] op_sel_hi:[1,0,1]
	s_waitcnt vmcnt(1)
	s_waitcnt lgkmcnt(7)
	v_pk_fma_f32 v[4:5], v[70:71], v[124:125], v[4:5] op_sel_hi:[1,0,1]
	v_pk_fma_f32 v[2:3], v[68:69], v[124:125], v[2:3] op_sel_hi:[1,0,1]
	s_waitcnt lgkmcnt(6)
	v_pk_fma_f32 v[8:9], v[70:71], v[126:127], v[8:9] op_sel_hi:[1,0,1]
	v_pk_fma_f32 v[6:7], v[68:69], v[126:127], v[6:7] op_sel_hi:[1,0,1]
	s_waitcnt lgkmcnt(5)
	v_pk_fma_f32 v[12:13], v[70:71], v[128:129], v[12:13] op_sel_hi:[1,0,1]
	v_pk_fma_f32 v[10:11], v[68:69], v[128:129], v[10:11] op_sel_hi:[1,0,1]
	s_waitcnt lgkmcnt(4)
	v_pk_fma_f32 v[16:17], v[70:71], v[130:131], v[16:17] op_sel_hi:[1,0,1]
	v_pk_fma_f32 v[14:15], v[68:69], v[130:131], v[14:15] op_sel_hi:[1,0,1]
	s_waitcnt vmcnt(0)
	s_waitcnt lgkmcnt(3)
	v_pk_fma_f32 v[4:5], v[74:75], v[132:133], v[4:5] op_sel_hi:[1,0,1]
	v_pk_fma_f32 v[2:3], v[72:73], v[132:133], v[2:3] op_sel_hi:[1,0,1]
	s_waitcnt lgkmcnt(2)
	v_pk_fma_f32 v[8:9], v[74:75], v[134:135], v[8:9] op_sel_hi:[1,0,1]
	v_pk_fma_f32 v[6:7], v[72:73], v[134:135], v[6:7] op_sel_hi:[1,0,1]
	s_waitcnt lgkmcnt(1)
	v_pk_fma_f32 v[12:13], v[74:75], v[136:137], v[12:13] op_sel_hi:[1,0,1]
	v_pk_fma_f32 v[10:11], v[72:73], v[136:137], v[10:11] op_sel_hi:[1,0,1]
	s_waitcnt lgkmcnt(0)
	v_pk_fma_f32 v[16:17], v[74:75], v[138:139], v[16:17] op_sel_hi:[1,0,1]
	v_pk_fma_f32 v[14:15], v[72:73], v[138:139], v[14:15] op_sel_hi:[1,0,1]
	s_mov_b32 s53, 64
	s_mov_b64 s[36:37], 0
	s_and_b64 vcc, exec, s[34:35]
	s_cbranch_vccz .LBB0_20
	s_mul_i32 s34, s52, 0x1800
	s_ashr_i32 s35, s34, 31
	s_lshl_b64 s[34:35], s[34:35], 2
	s_add_u32 s34, s4, s34
	s_addc_u32 s35, s5, s35
	ds_write_b128 v39, v[2:5]
	ds_write_b128 v39, v[6:9] offset:1024
	ds_write_b128 v39, v[10:13] offset:2048
	ds_write_b128 v39, v[14:17] offset:3072
	s_add_u32 s34, s34, s30
	s_waitcnt vmcnt(0) lgkmcnt(0)
	s_barrier
	s_addc_u32 s35, s35, s31
	v_lshl_add_u64 v[2:3], s[34:35], 0, v[18:19]
	v_mov_b32_e32 v6, 0
	s_and_b64 vcc, exec, s[12:13]
	v_mov_b32_e32 v7, 0
	s_cbranch_vccz .LBB0_25
	global_load_dword v7, v[2:3], off
